# phase A generic epilogue loop: staged-row and rsqrt LDS reads software-prefetched one iteration ahead
# speedup vs baseline: 1.0006x; 1.0006x over previous
; DI unsigned pk2(float lo, float hi) { unsigned r; asm("v_cvt_pk_bf16_f32 %0, %1, %2" : "=v"(r) : "v"(lo), "v"(hi)); return r; }
; DI float siluf_(float v) { return v / (1.f + __expf(-v)); }
; DI void phaseA_tile(const P& p, int layer, int mt, int nt, char* lds) {
;     ...
; #pragma unroll 2
;   for (int ps = 0; ps < 16; ++ps) {
;     const int lr = ps * 8 + wm * 4 + fq, row = row0 + lr;
;     const float r = rr[lr];
;     const float* tp = stg + lr * EPS + wn * 64;
;     const f32x4 v = *(const f32x4*)(tp + cc * 4) * r;
;     const int bb = isS ? ((row - NTP) >> 6) : (row >> 11);
;     const int t = isS ? ((row - NTP) & 63) : (row & 2047);
;     if (seg < 8) {
;       const int col = seg * 64 + cc * 4;
;       *(u32x2*)((bf16_t*)(p.ws + W_U) + (size_t)row * 512 + col) = u32x2{pk2(v.x, v.y), pk2(v.z, v.w)};
;       if (!isS) { if (t >= TP - 15) *(f32x4*)(out + O_PP + ((size_t)(layer * 16 + bb) * 15 + (t - (TP - 15))) * 512 + col) = v; }
;       else { if (t >= TS - 15) *(f32x4*)(out + O_PS + ((size_t)(layer * 8 + bb) * 15 + (t - (TS - 15))) * 512 + col) = v; }
;     } else if (seg < 16 || (seg >= 45 && seg < 53)) {
;       bf16_t* Z = (bf16_t*)(p.ws + (seg < 16 ? W_ZP : W_ZA)) + (size_t)row * 512 + (seg < 16 ? seg - 8 : seg - 45) * 64 + cc * 4;
;       *(u32x2*)Z = u32x2{pk2(siluf_(v.x), siluf_(v.y)), pk2(siluf_(v.z), siluf_(v.w))};
;     } else {
;       const int hc = (seg - 32) * 64 + cc * 4;
;       float* vo = isS ? out + O_VS + ((size_t)(layer * 8 + bb) * TS + t) * 512 + hc : out + O_VP + ((size_t)(layer * 16 + bb) * TP + t) * 512 + hc;
;       __builtin_nontemporal_store(v, (f32x4*)vo);
;     }
.LBB0_1264:
	s_and_b32 s0, s37, 0x7ffffff8
	s_cmp_eq_u32 s0, 8
	s_cselect_b64 s[0:1], -1, 0
	s_sub_i32 s4, s55, 40
	s_cmp_lt_u32 s4, 5
	s_cselect_b64 s[4:5], -1, 0
	s_or_b64 s[14:15], s[0:1], s[4:5]
	s_mov_b64 s[4:5], -1
	s_and_b64 vcc, exec, s[14:15]
	v_lshlrev_b32_e32 v126, 2, v89
	v_lshlrev_b32_e32 v70, 3, v89
	v_lshlrev_b32_e32 v72, 4, v89
	s_cbranch_vccnz .LBB0_1308
	s_lshl_b32 s22, s56, 2
	s_cmp_gt_i32 s55, 7
	s_cselect_b64 s[4:5], -1, 0
	s_cmp_lt_u32 s20, 16
	s_cselect_b64 s[16:17], -1, 0
	s_cmp_gt_u32 s20, 15
	s_cselect_b64 s[14:15], -1, 0
	s_cmp_lt_u32 s55, 45
	s_cselect_b64 s[18:19], -1, 0
	s_and_b64 s[14:15], s[14:15], s[18:19]
	s_and_b64 s[16:17], s[16:17], exec
	s_mov_b32 s16, 0xa34e000
	s_cselect_b32 s18, s16, 0x15c22000
	s_cselect_b32 s16, -8, 0xffffffd3
	s_add_i32 s16, s55, s16
	s_lshl_b32 s16, s16, 6
	s_ashr_i32 s17, s16, 31
	s_add_u32 s18, s90, s18
	s_addc_u32 s19, s91, 0
	s_lshl_b64 s[16:17], s[16:17], 1
	s_add_u32 s16, s18, s16
	v_lshl_or_b32 v66, s55, 6, v126
	s_addc_u32 s17, s19, s17
	v_mov_b32_e32 v71, v1
	v_ashrrev_i32_e32 v67, 31, v66
	v_readlane_b32 s24, v239, 21
	v_lshl_add_u64 v[80:81], s[16:17], 0, v[70:71]
	s_mul_i32 s16, s56, 0x840
	v_lshlrev_b64 v[68:69], 2, v[66:67]
	v_readlane_b32 s25, v239, 22
	v_mul_u32_u24_e32 v0, 0x210, v88
	s_add_i32 s16, s57, s16
	v_lshl_add_u64 v[76:77], s[24:25], 0, v[68:69]
	v_readlane_b32 s24, v239, 23
	v_add3_u32 v71, s16, v0, v72
	s_lshl_b32 s16, s56, 4
	v_or_b32_e32 v73, s22, v88
	v_add_u32_e32 v74, 0xfffff800, v66
	v_readlane_b32 s25, v239, 24
	s_add_i32 s16, s16, 0x10820
	s_add_i32 s22, s22, s10
	v_ashrrev_i32_e32 v75, 31, v74
	v_lshl_add_u64 v[78:79], s[24:25], 0, v[68:69]
	s_mov_b32 s21, 0
	v_lshl_add_u64 v[82:83], v[66:67], 1, s[58:59]
	v_or_b32_e32 v90, s16, v127
	v_add_u32_e32 v91, s22, v88
	v_subrev_u32_e32 v0, 32, v90
	ds_read_b128 v[2:5], v71
	ds_read_b32 v10, v0
	ds_read_b32 v11, v90
	ds_read_b128 v[6:9], v71 offset:4224
	s_branch .LBB0_1268

; DI void phaseA_tile(const P& p, int layer, int mt, int nt, char* lds) {
;     ...
;     const int lr = ps * 8 + wm * 4 + fq, row = row0 + lr;
;     const float r = rr[lr];
;     const float* tp = stg + lr * EPS + wn * 64;
;     const f32x4 v = *(const f32x4*)(tp + cc * 4) * r;
.LBB0_1268:
	s_waitcnt lgkmcnt(2)
	v_mov_b32_e32 v66, v2
	v_mov_b32_e32 v67, v3
	v_mov_b32_e32 v68, v4
	v_mov_b32_e32 v69, v5
	v_mov_b32_e32 v0, v10
	ds_read_b128 v[2:5], v71 offset:8448
	ds_read_b32 v10, v90 offset:32
	v_add_u32_e32 v84, s21, v91
	v_add_u32_e32 v93, s21, v73
	v_ashrrev_i32_e32 v96, 11, v84
	v_and_b32_e32 v95, 63, v93
	v_pk_mul_f32 v[68:69], v[68:69], v[0:1] op_sel_hi:[1,0]
	v_pk_mul_f32 v[66:67], v[66:67], v[0:1] op_sel_hi:[1,0]
	v_add_u32_e32 v0, 0xffff8000, v84
	v_ashrrev_i32_e32 v94, 6, v0
	v_and_b32_e32 v97, 0x7ff, v84
	s_mov_b64 s[16:17], -1
	s_and_b64 vcc, exec, s[4:5]
	s_cbranch_vccz .LBB0_1279
	s_and_b64 vcc, exec, s[14:15]
	s_cbranch_vccz .LBB0_1276
	s_and_b64 vcc, exec, s[12:13]
	s_cbranch_vccz .LBB0_1272
	v_add_u32_e32 v86, s34, v96
	s_mov_b64 s[16:17], 0

; DI void phaseA_tile(const P& p, int layer, int mt, int nt, char* lds) {
;     ...
;     const int lr = ps * 8 + wm * 4 + fq, row = row0 + lr;
;     const float r = rr[lr];
;     const float* tp = stg + lr * EPS + wn * 64;
;     const f32x4 v = *(const f32x4*)(tp + cc * 4) * r;
.LBB0_1288:
	s_waitcnt lgkmcnt(2)
	v_mov_b32_e32 v66, v6
	v_mov_b32_e32 v67, v7
	v_mov_b32_e32 v68, v8
	v_mov_b32_e32 v69, v9
	v_mov_b32_e32 v0, v11
	ds_read_b32 v11, v90 offset:64
	ds_read_b128 v[6:9], v71 offset:12672
	v_add_u32_e32 v85, 8, v93
	v_add_u32_e32 v86, 8, v84
	v_ashrrev_i32_e32 v95, 11, v86
	v_and_b32_e32 v94, 63, v85
	v_pk_mul_f32 v[68:69], v[68:69], v[0:1] op_sel_hi:[1,0]
	v_pk_mul_f32 v[66:67], v[66:67], v[0:1] op_sel_hi:[1,0]
	v_add_u32_e32 v0, 0xffff8008, v84
	v_ashrrev_i32_e32 v93, 6, v0
	v_and_b32_e32 v96, 0x7ff, v86
	s_andn2_b64 vcc, exec, s[4:5]
	s_mov_b64 s[16:17], -1
	s_cbranch_vccnz .LBB0_1299
	s_andn2_b64 vcc, exec, s[14:15]
	s_cbranch_vccnz .LBB0_1296
	s_andn2_b64 vcc, exec, s[12:13]
	s_cbranch_vccnz .LBB0_1292
	v_add_u32_e32 v84, s34, v95
	s_mov_b64 s[16:17], 0

; DI unsigned pk2(float lo, float hi) { unsigned r; asm("v_cvt_pk_bf16_f32 %0, %1, %2" : "=v"(r) : "v"(lo), "v"(hi)); return r; }
; DI float siluf_(float v) { return v / (1.f + __expf(-v)); }
; DI void phaseA_tile(const P& p, int layer, int mt, int nt, char* lds) {
;     ...
; #pragma unroll 2
;   for (int ps = 0; ps < 16; ++ps) {
;     const int lr = ps * 8 + wm * 4 + fq, row = row0 + lr;
;     const float r = rr[lr];
;     const float* tp = stg + lr * EPS + wn * 64;
;     const f32x4 v = *(const f32x4*)(tp + cc * 4) * r;
;     const int bb = isS ? ((row - NTP) >> 6) : (row >> 11);
;     const int t = isS ? ((row - NTP) & 63) : (row & 2047);
;     if (seg < 8) {
;       const int col = seg * 64 + cc * 4;
;       *(u32x2*)((bf16_t*)(p.ws + W_U) + (size_t)row * 512 + col) = u32x2{pk2(v.x, v.y), pk2(v.z, v.w)};
;       if (!isS) { if (t >= TP - 15) *(f32x4*)(out + O_PP + ((size_t)(layer * 16 + bb) * 15 + (t - (TP - 15))) * 512 + col) = v; }
;       else { if (t >= TS - 15) *(f32x4*)(out + O_PS + ((size_t)(layer * 8 + bb) * 15 + (t - (TS - 15))) * 512 + col) = v; }
;     } else if (seg < 16 || (seg >= 45 && seg < 53)) {
;       bf16_t* Z = (bf16_t*)(p.ws + (seg < 16 ? W_ZP : W_ZA)) + (size_t)row * 512 + (seg < 16 ? seg - 8 : seg - 45) * 64 + cc * 4;
;       *(u32x2*)Z = u32x2{pk2(siluf_(v.x), siluf_(v.y)), pk2(siluf_(v.z), siluf_(v.w))};
;     } else {
;       const int hc = (seg - 32) * 64 + cc * 4;
;       float* vo = isS ? out + O_VS + ((size_t)(layer * 8 + bb) * TS + t) * 512 + hc : out + O_VP + ((size_t)(layer * 16 + bb) * TP + t) * 512 + hc;
;       __builtin_nontemporal_store(v, (f32x4*)vo);
;     }
;   }
.LBB0_1307:
	s_waitcnt lgkmcnt(0)
	s_mov_b64 s[4:5], 0
